# lever 4 extended: static s_setprio 1 for waves 4-7 across the HGRN chunk loop as well (on top of the RWKV one)
# baseline (speedup 1.0000x reference)
; #define LAS __attribute__((address_space(3)))
; __device__ __forceinline__ float frcp(float x) { return __builtin_amdgcn_rcpf(x); }
; #define HG_ISSUE(t0n) do { _Pragma("unroll") for (int i = 0; i < 16; ++i) { const int tk = (t0n) + (dir ? 63 - (i0 + i) : (i0 + i)); const bf16_t* pr = Pb + (size_t)tk * HGP + h * 128 + dcol; \
;         rq[i] = pr[0]; rf[i] = pr[1024 * (1 + dir)]; rv[i] = pr[3072]; } } while (0)
; __device__ __forceinline__ void hgrn_chain(LAS unsigned char* lds, int cid, bf16_t* P1, const float* hg_lb, bf16_t* Ob, int ldo, int ocbase, int ocdir) {
;     ...
;     for (int e = tid; e < 128 * HLD / 2; e += 512) ((LAS unsigned*)ST)[e] = 0u;
;     const int dcol = tid & 127, qtr = tid >> 7, i0 = qtr * 16;
;     const float lbv = frcp(1.0f + __expf(hg_lb[h * 128 + dcol] - hg_lb[1024 + h * 128 + dcol]));
;     f32x4 st[8];
; #pragma unroll
;     for (int i = 0; i < 8; ++i) st[i] = (f32x4){0.f, 0.f, 0.f, 0.f};
;     bf16_t* Pb = P1 + (size_t)b * SEQ * HGP;
;     __syncthreads();
;     unsigned short rq[16], rf[16], rv[16];
;     ...
;     HG_ISSUE((dir ? 63 : 0) * 64);
.LBB0_1713:
	v_add_u32_e32 v1, 0x200, v1
	v_cmp_lt_u32_e32 vcc, s38, v1
	ds_write_b32 v0, v43
	s_or_b64 s[34:35], vcc, s[34:35]
	v_add_u32_e32 v0, 0x800, v0
	s_andn2_b64 exec, exec, s[34:35]
	s_cbranch_execnz .LBB0_1713
	s_or_b64 exec, exec, s[34:35]
	s_lshl_b32 s30, s41, 6
	s_and_b32 s30, s30, 0x380
	v_or_b32_e32 v0, s30, v40
	v_lshlrev_b32_e32 v42, 2, v0
	v_lshl_add_u64 v[0:1], s[24:25], 0, v[42:43]
	v_add_co_u32_e32 v0, vcc, 0x1000, v0
	s_ashr_i32 s34, s41, 4
	s_nop 0
	v_addc_co_u32_e32 v1, vcc, 0, v1, vcc
	global_load_dword v38, v42, s[24:25]
	global_load_dword v39, v[0:1], off
	s_and_b32 s37, s41, 1
	s_ashr_i32 s35, s34, 31
	s_mul_i32 s25, s34, 0x2800000
	s_mul_hi_i32 s24, s34, 0x2800000
	s_add_u32 s42, s72, s25
	s_addc_u32 s43, s73, s24
	s_cmp_eq_u32 s37, 0
	s_cselect_b64 s[24:25], -1, 0
	s_lshl_b32 s36, s30, 1
	s_add_u32 s42, s42, s36
	s_addc_u32 s43, s43, 0
	v_lshlrev_b32_e32 v42, 1, v40
	v_cndmask_b32_e64 v0, v104, v41, s[24:25]
	v_lshl_add_u64 v[48:49], s[42:43], 0, v[42:43]
	v_mul_u32_u24_e32 v42, 0x2800, v0
	v_lshl_add_u64 v[0:1], v[48:49], 0, v[42:43]
	v_cndmask_b32_e64 v4, v106, v105, s[24:25]
	v_add_co_u32_e32 v2, vcc, s39, v0
	v_mul_u32_u24_e32 v42, 0x2800, v4
	s_nop 0
	v_addc_co_u32_e32 v3, vcc, 0, v1, vcc
	v_lshl_add_u64 v[4:5], v[48:49], 0, v[42:43]
	v_add_co_u32_e32 v6, vcc, s39, v4
	s_waitcnt lgkmcnt(0)
	s_barrier
	v_addc_co_u32_e32 v7, vcc, 0, v5, vcc
	global_load_ushort v45, v[2:3], off offset:2048
	global_load_ushort v47, v[6:7], off offset:2048
	v_cndmask_b32_e64 v2, v108, v107, s[24:25]
	v_mul_u32_u24_e32 v42, 0x2800, v2
	v_lshl_add_u64 v[2:3], v[48:49], 0, v[42:43]
	v_cndmask_b32_e64 v8, v110, v109, s[24:25]
	v_add_co_u32_e32 v6, vcc, s39, v2
	v_mul_u32_u24_e32 v42, 0x2800, v8
	s_nop 0
	v_addc_co_u32_e32 v7, vcc, 0, v3, vcc
	v_lshl_add_u64 v[8:9], v[48:49], 0, v[42:43]
	v_cndmask_b32_e64 v12, v112, v111, s[24:25]
	v_add_co_u32_e32 v10, vcc, s39, v8
	v_mul_u32_u24_e32 v42, 0x2800, v12
	s_nop 0
	v_addc_co_u32_e32 v11, vcc, 0, v9, vcc
	v_lshl_add_u64 v[12:13], v[48:49], 0, v[42:43]
	v_add_co_u32_e32 v14, vcc, s39, v12
	v_cndmask_b32_e64 v18, v118, v117, s[24:25]
	s_nop 0
	v_addc_co_u32_e32 v15, vcc, 0, v13, vcc
	global_load_ushort v50, v[6:7], off offset:2048
	global_load_ushort v51, v[10:11], off offset:2048
	global_load_ushort v52, v[14:15], off offset:2048
	v_cndmask_b32_e64 v6, v114, v113, s[24:25]
	v_mul_u32_u24_e32 v42, 0x2800, v6
	v_lshl_add_u64 v[6:7], v[48:49], 0, v[42:43]
	v_cndmask_b32_e64 v14, v116, v115, s[24:25]
	v_add_co_u32_e32 v10, vcc, s39, v6
	v_mul_u32_u24_e32 v42, 0x2800, v14
	s_nop 0
	v_addc_co_u32_e32 v11, vcc, 0, v7, vcc
	v_lshl_add_u64 v[14:15], v[48:49], 0, v[42:43]
	v_add_co_u32_e32 v16, vcc, s39, v14
	v_mul_u32_u24_e32 v42, 0x2800, v18
	s_nop 0
	v_addc_co_u32_e32 v17, vcc, 0, v15, vcc
	v_lshl_add_u64 v[18:19], v[48:49], 0, v[42:43]
	v_add_co_u32_e32 v20, vcc, s39, v18
	v_cndmask_b32_e64 v24, v126, v125, s[24:25]
	s_nop 0
	v_addc_co_u32_e32 v21, vcc, 0, v19, vcc
	global_load_ushort v53, v[10:11], off offset:2048
	global_load_ushort v54, v[16:17], off offset:2048
	global_load_ushort v55, v[20:21], off offset:2048
	v_cndmask_b32_e64 v10, v120, v119, s[24:25]
	v_mul_u32_u24_e32 v42, 0x2800, v10
	v_lshl_add_u64 v[10:11], v[48:49], 0, v[42:43]
	v_cndmask_b32_e64 v20, v122, v121, s[24:25]
	v_add_co_u32_e32 v16, vcc, s39, v10
	v_mul_u32_u24_e32 v42, 0x2800, v20
	s_nop 0
	v_addc_co_u32_e32 v17, vcc, 0, v11, vcc
	v_lshl_add_u64 v[20:21], v[48:49], 0, v[42:43]
	v_add_co_u32_e32 v22, vcc, s39, v20
	v_cndmask_b32_e64 v28, v128, v127, s[24:25]
	s_nop 0
	v_addc_co_u32_e32 v23, vcc, 0, v21, vcc
	global_load_ushort v56, v[16:17], off offset:2048
	global_load_ushort v57, v[22:23], off offset:2048
	v_cndmask_b32_e64 v16, v124, v123, s[24:25]
	v_mul_u32_u24_e32 v42, 0x2800, v16
	v_lshl_add_u64 v[16:17], v[48:49], 0, v[42:43]
	v_add_co_u32_e32 v22, vcc, s39, v16
	v_mul_u32_u24_e32 v42, 0x2800, v24
	s_nop 0
	v_addc_co_u32_e32 v23, vcc, 0, v17, vcc
	v_lshl_add_u64 v[24:25], v[48:49], 0, v[42:43]
	v_add_co_u32_e32 v26, vcc, s39, v24
	v_mul_u32_u24_e32 v42, 0x2800, v28
	s_nop 0
	v_addc_co_u32_e32 v27, vcc, 0, v25, vcc
	v_lshl_add_u64 v[28:29], v[48:49], 0, v[42:43]
	v_add_co_u32_e32 v30, vcc, s39, v28
	v_cndmask_b32_e64 v34, v134, v133, s[24:25]
	s_nop 0
	v_addc_co_u32_e32 v31, vcc, 0, v29, vcc
	global_load_ushort v58, v[22:23], off offset:2048
	global_load_ushort v59, v[26:27], off offset:2048
	global_load_ushort v60, v[30:31], off offset:2048
	v_cndmask_b32_e64 v22, v130, v129, s[24:25]
	v_mul_u32_u24_e32 v42, 0x2800, v22
	v_lshl_add_u64 v[22:23], v[48:49], 0, v[42:43]
	v_cndmask_b32_e64 v30, v132, v131, s[24:25]
	v_add_co_u32_e32 v26, vcc, s39, v22
	v_mul_u32_u24_e32 v42, 0x2800, v30
	s_nop 0
	v_addc_co_u32_e32 v27, vcc, 0, v23, vcc
	v_lshl_add_u64 v[30:31], v[48:49], 0, v[42:43]
	v_add_co_u32_e32 v32, vcc, s39, v30
	v_mul_u32_u24_e32 v42, 0x2800, v34
	s_nop 0
	v_addc_co_u32_e32 v33, vcc, 0, v31, vcc
	v_lshl_add_u64 v[34:35], v[48:49], 0, v[42:43]
	v_add_co_u32_e32 v36, vcc, s39, v34
	s_lshl_b32 s30, s37, 11
	s_nop 0
	v_addc_co_u32_e32 v37, vcc, 0, v35, vcc
	global_load_ushort v42, v[26:27], off offset:2048
	global_load_ushort v61, v[32:33], off offset:2048
	global_load_ushort v62, v[36:37], off offset:2048
	v_lshl_add_u64 v[26:27], v[6:7], 0, s[30:31]
	v_lshl_add_u64 v[32:33], v[14:15], 0, s[30:31]
	v_lshl_add_u64 v[36:37], v[18:19], 0, s[30:31]
	global_load_ushort v207, v[26:27], off offset:2048
	global_load_ushort v209, v[14:15], off
	global_load_ushort v210, v[32:33], off offset:2048
	global_load_ushort v211, v[18:19], off
	global_load_ushort v212, v[36:37], off offset:2048
	v_lshl_add_u64 v[14:15], v[22:23], 0, s[30:31]
	v_lshl_add_u64 v[18:19], v[30:31], 0, s[30:31]
	v_lshl_add_u64 v[26:27], v[34:35], 0, s[30:31]
	global_load_ushort v219, v[14:15], off offset:2048
	global_load_ushort v220, v[30:31], off
	global_load_ushort v221, v[18:19], off offset:2048
	global_load_ushort v222, v[34:35], off
	global_load_ushort v223, v[26:27], off offset:2048
	s_waitcnt vmcnt(26)
; #define LAS __attribute__((address_space(3)))
; __device__ __forceinline__ unsigned pk2(float lo, float hi) { const f32x2 v = {lo, hi}; return __builtin_bit_cast(unsigned, __builtin_convertvector(v, bf16x2_t)); }
; __device__ __forceinline__ float frcp(float x) { return __builtin_amdgcn_rcpf(x); }
; __device__ __forceinline__ float sigmoidf_(float x) { return frcp(1.0f + __expf(-x)); }
; __device__ __forceinline__ f32x4 mfma16(bf16x8 bfrag, bf16x8 afrag, f32x4 acc) { return __builtin_amdgcn_mfma_f32_16x16x32_bf16(bfrag, afrag, acc, 0, 0, 0); }
; #define HG_ISSUE(t0n) do { _Pragma("unroll") for (int i = 0; i < 16; ++i) { const int tk = (t0n) + (dir ? 63 - (i0 + i) : (i0 + i)); const bf16_t* pr = Pb + (size_t)tk * HGP + h * 128 + dcol; \
;         rq[i] = pr[0]; rf[i] = pr[1024 * (1 + dir)]; rv[i] = pr[3072]; } } while (0)
; __device__ __forceinline__ void hgrn_chain(LAS unsigned char* lds, int cid, bf16_t* P1, const float* hg_lb, bf16_t* Ob, int ldo, int ocbase, int ocdir) {
;     ...
;     const float lbv = frcp(1.0f + __expf(hg_lb[h * 128 + dcol] - hg_lb[1024 + h * 128 + dcol]));
;     f32x4 st[8];
; #pragma unroll
;     for (int i = 0; i < 8; ++i) st[i] = (f32x4){0.f, 0.f, 0.f, 0.f};
;     bf16_t* Pb = P1 + (size_t)b * SEQ * HGP;
;     __syncthreads();
;     unsigned short rq[16], rf[16], rv[16];
;     ...
;     HG_ISSUE((dir ? 63 : 0) * 64);
;     for (int cc = 0; cc < 64; ++cc) {
;         const int t0 = (dir ? 63 - cc : cc) * 64;
;         float gq[16], gk[16], gc[16]; float run = 1.0f;
; #pragma unroll
;         for (int i = 0; i < 16; ++i) { const float q = bf2f(rq[i]), fr_ = bf2f(rf[i]);
;             const float f = lbv + (1.0f - lbv) * sigmoidf_(fr_); run *= f; gq[i] = q; gk[i] = 1.0f - f; gc[i] = run; }
;     ...
;         { const int mt = w >> 1;
; #pragma unroll
;           for (int n2 = 0; n2 < 2; ++n2) { const int nt = (w & 1) * 2 + n2; f32x4 acc = (f32x4){0.f, 0.f, 0.f, 0.f};
; #pragma unroll
;               for (int ks = 0; ks < 4; ++ks) acc = mfma16(ldsfrag(KE, HLD, nt * 16, ks * 32, fr, fq), ldsfrag(QE, HLD, mt * 16, ks * 32, fr, fq), acc);
;               const int lrow = mt * 16 + fr; float mv[4];
; #pragma unroll
;               for (int i = 0; i < 4; ++i) { const int s = nt * 16 + fq * 4 + i; mv[i] = (s <= lrow) ? acc[i] : 0.f; }
;               u32x2 o; o.x = pk2(mv[0], mv[1]); o.y = pk2(mv[2], mv[3]); *(LAS u32x2*)(AT + lrow * HLS + nt * 16 + fq * 4) = o; } }
	v_sub_f32_e32 v14, v38, v39
	v_mul_f32_e32 v30, 0x3fb8aa3b, v14
	v_lshl_add_u64 v[14:15], v[0:1], 0, s[30:31]
	v_lshl_add_u64 v[18:19], v[4:5], 0, s[30:31]
	v_lshl_add_u64 v[26:27], v[2:3], 0, s[30:31]
	global_load_ushort v179, v[0:1], off
	global_load_ushort v180, v[14:15], off offset:2048
	global_load_ushort v181, v[4:5], off
	global_load_ushort v182, v[18:19], off offset:2048
	global_load_ushort v183, v[2:3], off
	global_load_ushort v185, v[26:27], off offset:2048
	v_lshl_add_u64 v[0:1], v[8:9], 0, s[30:31]
	v_lshl_add_u64 v[2:3], v[12:13], 0, s[30:31]
	global_load_ushort v203, v[8:9], off
	global_load_ushort v204, v[0:1], off offset:2048
	global_load_ushort v205, v[12:13], off
	global_load_ushort v206, v[2:3], off offset:2048
	global_load_ushort v208, v[6:7], off
	v_lshl_add_u64 v[0:1], v[10:11], 0, s[30:31]
	v_lshl_add_u64 v[2:3], v[20:21], 0, s[30:31]
	v_lshl_add_u64 v[4:5], v[16:17], 0, s[30:31]
	global_load_ushort v213, v[10:11], off
	global_load_ushort v214, v[0:1], off offset:2048
	global_load_ushort v215, v[20:21], off
	global_load_ushort v216, v[2:3], off offset:2048
	global_load_ushort v217, v[16:17], off
	global_load_ushort v218, v[4:5], off offset:2048
	v_lshl_add_u64 v[0:1], v[24:25], 0, s[30:31]
	v_lshl_add_u64 v[2:3], v[28:29], 0, s[30:31]
	global_load_ushort v224, v[24:25], off
	global_load_ushort v225, v[0:1], off offset:2048
	global_load_ushort v226, v[28:29], off
	global_load_ushort v227, v[2:3], off offset:2048
	global_load_ushort v228, v[22:23], off
	v_exp_f32_e32 v0, v30
	s_lshl_b32 s44, s37, 10
	s_lshl_b64 s[34:35], s[34:35], 12
	s_add_u32 s30, s72, s30
	v_add_f32_e32 v0, 1.0, v0
	s_waitcnt vmcnt(44)
	v_lshl_or_b32 v33, v51, 16, v50
	v_rcp_f32_e32 v50, v0
	s_addc_u32 s37, s73, 0
	s_add_u32 s36, s30, s36
	v_lshl_or_b32 v32, v47, 16, v45
	s_addc_u32 s37, s37, 0
	v_mov_b32_e32 v45, v43
	v_lshl_add_u64 v[0:1], s[36:37], 0, v[44:45]
	v_mov_b32_e32 v47, v43
	s_waitcnt vmcnt(42)
	v_lshl_or_b32 v34, v53, 16, v52
	s_waitcnt vmcnt(40)
	v_lshl_or_b32 v35, v55, 16, v54
	v_sub_f32_e32 v52, 1.0, v50
	v_lshl_add_u64 v[54:55], v[0:1], 0, v[46:47]
	v_mov_b32_e32 v0, 0
	s_mov_b32 s42, 1
	s_waitcnt vmcnt(38)
	v_lshl_or_b32 v36, v57, 16, v56
	v_cndmask_b32_e64 v184, v142, v140, s[24:25]
	v_cndmask_b32_e64 v186, v145, v41, s[24:25]
	v_cndmask_b32_e64 v187, v146, v105, s[24:25]
	v_cndmask_b32_e64 v188, v147, v107, s[24:25]
	v_cndmask_b32_e64 v189, v148, v109, s[24:25]
	v_cndmask_b32_e64 v190, v149, v111, s[24:25]
	v_cndmask_b32_e64 v191, v150, v113, s[24:25]
	v_cndmask_b32_e64 v192, v151, v115, s[24:25]
	v_cndmask_b32_e64 v193, v152, v117, s[24:25]
	v_cndmask_b32_e64 v194, v153, v119, s[24:25]
	v_cndmask_b32_e64 v195, v154, v121, s[24:25]
	s_waitcnt vmcnt(36)
	v_lshl_or_b32 v37, v59, 16, v58
	v_cndmask_b32_e64 v196, v155, v123, s[24:25]
	v_cndmask_b32_e64 v197, v156, v125, s[24:25]
	v_cndmask_b32_e64 v198, v157, v127, s[24:25]
	v_cndmask_b32_e64 v199, v158, v129, s[24:25]
	v_cndmask_b32_e64 v201, v159, v131, s[24:25]
	v_cndmask_b32_e64 v202, v160, v133, s[24:25]
	v_mov_b32_e32 v51, v50
	v_mov_b32_e32 v53, v52
	s_mov_b32 s43, 62
	s_lshl_b32 s30, s44, 1
	v_mov_b32_e32 v1, v0
	v_mov_b32_e32 v2, v0
	v_mov_b32_e32 v3, v0
	v_mov_b32_e32 v4, v0
	v_mov_b32_e32 v5, v0
	v_mov_b32_e32 v6, v0
	v_mov_b32_e32 v7, v0
	v_mov_b32_e32 v8, v0
	v_mov_b32_e32 v9, v0
	v_mov_b32_e32 v10, v0
	s_waitcnt vmcnt(34)
	v_lshl_or_b32 v38, v42, 16, v60
	v_mov_b32_e32 v11, v0
	s_waitcnt vmcnt(32)
	v_lshl_or_b32 v39, v62, 16, v61
	v_mov_b32_e32 v16, v0
	v_mov_b32_e32 v17, v0
	v_mov_b32_e32 v18, v0
	v_mov_b32_e32 v19, v0
	v_mov_b32_e32 v12, v0
	v_mov_b32_e32 v13, v0
	v_mov_b32_e32 v14, v0
	v_mov_b32_e32 v15, v0
	v_mov_b32_e32 v24, v0
	v_mov_b32_e32 v25, v0
	v_mov_b32_e32 v26, v0
	v_mov_b32_e32 v27, v0
	v_mov_b32_e32 v20, v0
	v_mov_b32_e32 v21, v0
	v_mov_b32_e32 v22, v0
	v_mov_b32_e32 v23, v0
	v_mov_b32_e32 v28, v0
	v_mov_b32_e32 v29, v0
	v_mov_b32_e32 v30, v0
	v_mov_b32_e32 v31, v0
	v_readfirstlane_b32 s36, v200
	s_nop 3
	s_cmpk_lt_u32 s36, 0x100
	s_cbranch_scc1 .Lhg_prio_done
	s_setprio 1
.Lhg_prio_done:
	s_branch .LBB0_1716
.LBB0_1715:
	s_waitcnt lgkmcnt(0)
	s_barrier
	ds_read_b128 v[56:59], v163 offset:17408
	ds_read_b128 v[60:63], v163 offset:17472
	ds_read_b128 v[64:67], v164
	ds_read_b128 v[68:71], v164 offset:64
	s_waitcnt lgkmcnt(1)
	v_mfma_f32_16x16x32_bf16 v[56:59], v[56:59], v[64:67], 0
	ds_read_b128 v[72:75], v163 offset:17536
	ds_read_b128 v[76:79], v163 offset:17600
	s_add_i32 s44, s42, -1
	s_add_i32 s45, s43, 1
	s_waitcnt lgkmcnt(2)
	v_mfma_f32_16x16x32_bf16 v[56:59], v[60:63], v[68:71], v[56:59]
	ds_read_b128 v[60:63], v164 offset:128
	ds_read_b128 v[80:83], v164 offset:192
	s_and_b64 s[36:37], s[24:25], exec
	s_cselect_b32 s36, s44, s45
	s_waitcnt lgkmcnt(1)
	v_mfma_f32_16x16x32_bf16 v[56:59], v[72:75], v[60:63], v[56:59]
	s_add_i32 s43, s43, -1
	s_add_i32 s42, s42, 1
	s_cmp_lg_u32 s43, -2
	s_waitcnt lgkmcnt(0)
	v_mfma_f32_16x16x32_bf16 v[56:59], v[76:79], v[80:83], v[56:59]
	s_nop 7
	v_cndmask_b32_e64 v42, v56, 0, s[8:9]
	v_cndmask_b32_e64 v45, 0, v57, s[10:11]
	v_cndmask_b32_e64 v47, v58, 0, s[12:13]
	v_cndmask_b32_e64 v57, v59, 0, s[14:15]
	v_cvt_pk_bf16_f32 v56, v42, v45
	v_cvt_pk_bf16_f32 v57, v47, v57
	ds_write_b64 v165, v[56:57]
	ds_read_b128 v[56:59], v166 offset:17408
	ds_read_b128 v[72:75], v166 offset:17472
	s_waitcnt lgkmcnt(1)
	v_mfma_f32_16x16x32_bf16 v[56:59], v[56:59], v[64:67], 0
	ds_read_b128 v[64:67], v166 offset:17536
	s_waitcnt lgkmcnt(1)
	v_mfma_f32_16x16x32_bf16 v[56:59], v[72:75], v[68:71], v[56:59]
	ds_read_b128 v[68:71], v166 offset:17600
	s_waitcnt lgkmcnt(1)
	v_mfma_f32_16x16x32_bf16 v[56:59], v[64:67], v[60:63], v[56:59]
	s_waitcnt lgkmcnt(0)
	v_mfma_f32_16x16x32_bf16 v[56:59], v[68:71], v[80:83], v[56:59]
	s_nop 7
	v_cndmask_b32_e64 v42, v56, 0, s[16:17]
	v_cndmask_b32_e64 v45, 0, v57, s[18:19]
	v_cndmask_b32_e64 v47, v58, 0, s[20:21]
	v_cndmask_b32_e64 v57, v59, 0, s[22:23]
	v_cvt_pk_bf16_f32 v56, v42, v45
	v_cvt_pk_bf16_f32 v57, v47, v57
	ds_write_b64 v167, v[56:57]
	s_waitcnt lgkmcnt(0)
	s_barrier
; #define LAS __attribute__((address_space(3)))
; __device__ __forceinline__ unsigned pk2(float lo, float hi) { const f32x2 v = {lo, hi}; return __builtin_bit_cast(unsigned, __builtin_convertvector(v, bf16x2_t)); }
; __device__ __forceinline__ f32x4 mfma16(bf16x8 bfrag, bf16x8 afrag, f32x4 acc) { return __builtin_amdgcn_mfma_f32_16x16x32_bf16(bfrag, afrag, acc, 0, 0, 0); }
; __device__ __forceinline__ void hgrn_chain(LAS unsigned char* lds, int cid, bf16_t* P1, const float* hg_lb, bf16_t* Ob, int ldo, int ocbase, int ocdir) {
;     ...
;         { const int mt = w >> 1;
; #pragma unroll
;           for (int n4 = 0; n4 < 4; ++n4) { const int nt = (w & 1) * 4 + n4; f32x4 acc = (f32x4){0.f, 0.f, 0.f, 0.f};
; #pragma unroll
;               for (int ks = 0; ks < 2; ++ks) acc = mfma16(ldsfrag(VT, HLS, nt * 16, ks * 32, fr, fq), ldsfrag(AT, HLS, mt * 16, ks * 32, fr, fq), acc);
; #pragma unroll
;               for (int ks = 0; ks < 4; ++ks) acc = mfma16(ldsfrag(ST, HLD, nt * 16, ks * 32, fr, fq), ldsfrag(QE, HLD, mt * 16, ks * 32, fr, fq), acc);
;               const int i = mt * 16 + fr, tk = t0 + (dir ? 63 - i : i);
;               u32x2 o; o.x = pk2(acc[0], acc[1]); o.y = pk2(acc[2], acc[3]);
;               *(u32x2*)(Ob + ((size_t)b * SEQ + tk) * ldo + ocbase + ocdir * dir + h * 128 + nt * 16 + fq * 4) = o; } }
; #pragma unroll
;         for (int nt = 0; nt < 8; ++nt) { const f32x4 el = *(const LAS f32x4*)(lastS + nt * 16 + fq * 4); st[nt] = st[nt] * el;
; #pragma unroll
;             for (int ks = 0; ks < 2; ++ks) st[nt] = mfma16(ldsfrag(KLT, HLS, nt * 16, ks * 32, fr, fq), ldsfrag(VT, HLS, w * 16, ks * 32, fr, fq), st[nt]); }
;         __syncthreads();
	ds_read_b128 v[56:59], v168 offset:53248
	v_add_u32_e32 v42, v141, v138
	ds_read_b128 v[60:63], v42
	ds_read_b128 v[64:67], v168 offset:53312
	ds_read_b128 v[68:71], v42 offset:64
	s_waitcnt lgkmcnt(2)
	v_mfma_f32_16x16x32_bf16 v[56:59], v[56:59], v[60:63], 0
	ds_read_b128 v[72:75], v170 offset:53248
	ds_read_b128 v[76:79], v170 offset:53312
	ds_read_b128 v[80:83], v172 offset:53248
	ds_read_b128 v[84:87], v172 offset:53312
	v_add_u32_e32 v42, 0x1cc00, v139
	s_waitcnt lgkmcnt(4)
	v_mfma_f32_16x16x32_bf16 v[56:59], v[64:67], v[68:71], v[56:59]
	ds_read_b128 v[64:67], v169
	s_waitcnt lgkmcnt(4)
	v_mfma_f32_16x16x32_bf16 v[72:75], v[72:75], v[60:63], 0
	s_waitcnt lgkmcnt(3)
	v_mfma_f32_16x16x32_bf16 v[72:75], v[76:79], v[68:71], v[72:75]
	ds_read_b128 v[76:79], v164
	ds_read_b128 v[88:91], v169 offset:64
	ds_read_b128 v[92:95], v164 offset:64
	s_waitcnt lgkmcnt(2)
	v_mfma_f32_16x16x32_bf16 v[56:59], v[64:67], v[76:79], v[56:59]
	ds_read_b128 v[64:67], v171
	ds_read_b128 v[96:99], v171 offset:64
	s_waitcnt lgkmcnt(1)
	v_mfma_f32_16x16x32_bf16 v[64:67], v[64:67], v[76:79], v[72:75]
	s_nop 2
	ds_read_b128 v[72:75], v169 offset:128
	v_mfma_f32_16x16x32_bf16 v[56:59], v[88:91], v[92:95], v[56:59]
	s_waitcnt lgkmcnt(1)
	v_mfma_f32_16x16x32_bf16 v[64:67], v[96:99], v[92:95], v[64:67]
	ds_read_b128 v[88:91], v164 offset:128
	ds_read_b128 v[96:99], v169 offset:192
	ds_read_b128 v[100:103], v164 offset:192
	s_waitcnt lgkmcnt(2)
	v_mfma_f32_16x16x32_bf16 v[56:59], v[72:75], v[88:91], v[56:59]
	ds_read_b128 v[72:75], v171 offset:128
	ds_read_b128 v[230:233], v171 offset:192
	s_waitcnt lgkmcnt(1)
	v_mfma_f32_16x16x32_bf16 v[64:67], v[72:75], v[88:91], v[64:67]
	ds_read_b128 v[72:75], v173
	v_mfma_f32_16x16x32_bf16 v[80:83], v[80:83], v[60:63], 0
	v_mfma_f32_16x16x32_bf16 v[80:83], v[84:87], v[68:71], v[80:83]
	ds_read_b128 v[84:87], v173 offset:64
	s_waitcnt lgkmcnt(1)
	v_mfma_f32_16x16x32_bf16 v[72:75], v[72:75], v[76:79], v[80:83]
	v_mfma_f32_16x16x32_bf16 v[56:59], v[96:99], v[100:103], v[56:59]
	s_nop 3
	ds_read_b128 v[80:83], v173 offset:128
	ds_read_b128 v[96:99], v173 offset:192
	s_waitcnt lgkmcnt(2)
	v_mfma_f32_16x16x32_bf16 v[72:75], v[84:87], v[92:95], v[72:75]
	ds_read_b128 v[84:87], v174 offset:53248
	s_waitcnt lgkmcnt(2)
	v_mfma_f32_16x16x32_bf16 v[72:75], v[80:83], v[88:91], v[72:75]
	ds_read_b128 v[80:83], v174 offset:53312
	s_waitcnt lgkmcnt(2)
	v_mfma_f32_16x16x32_bf16 v[72:75], v[96:99], v[100:103], v[72:75]
	ds_read_b128 v[96:99], v175
	s_waitcnt lgkmcnt(2)
	v_mfma_f32_16x16x32_bf16 v[60:63], v[84:87], v[60:63], 0
	v_cvt_pk_bf16_f32 v84, v56, v57
	v_cvt_pk_bf16_f32 v85, v58, v59
	ds_read_b128 v[56:59], v175 offset:64
	s_waitcnt lgkmcnt(2)
	v_mfma_f32_16x16x32_bf16 v[60:63], v[80:83], v[68:71], v[60:63]
	ds_read_b128 v[68:71], v175 offset:128
	s_waitcnt lgkmcnt(2)
	v_mfma_f32_16x16x32_bf16 v[60:63], v[96:99], v[76:79], v[60:63]
	ds_read_b128 v[76:79], v175 offset:192
	v_mfma_f32_16x16x32_bf16 v[64:67], v[230:233], v[100:103], v[64:67]
	v_lshl_add_u32 v230, s36, 6, v184
	v_ashrrev_i32_e32 v231, 31, v230
	v_lshl_add_u64 v[230:231], s[34:35], 0, v[230:231]
	s_waitcnt lgkmcnt(2)
	v_mfma_f32_16x16x32_bf16 v[56:59], v[56:59], v[92:95], v[60:63]
	v_mad_u64_u32 v[80:81], s[36:37], v230, s40, v[54:55]
	v_mad_i32_i24 v81, v231, s40, v81
	s_nop 0
	v_cvt_pk_bf16_f32 v60, v64, v65
	v_cvt_pk_bf16_f32 v61, v66, v67
	global_store_dwordx2 v[80:81], v[60:61], off offset:2080
	v_cvt_pk_bf16_f32 v60, v72, v73
	v_cvt_pk_bf16_f32 v61, v74, v75
	global_store_dwordx2 v[80:81], v[60:61], off offset:2112
	ds_read_b128 v[60:63], v42
	s_waitcnt lgkmcnt(2)
	v_mfma_f32_16x16x32_bf16 v[56:59], v[68:71], v[88:91], v[56:59]
	global_store_dwordx2 v[80:81], v[84:85], off offset:2048
	s_waitcnt lgkmcnt(0)
	v_pk_mul_f32 v[0:1], v[0:1], v[60:61]
	v_mfma_f32_16x16x32_bf16 v[56:59], v[76:79], v[100:103], v[56:59]
	v_mul_f32_e64 v2, v2, v62
	v_mul_f32_e64 v3, v3, v63
	s_nop 5
	v_cvt_pk_bf16_f32 v56, v56, v57
	v_cvt_pk_bf16_f32 v57, v58, v59
	global_store_dwordx2 v[80:81], v[56:57], off offset:2144
	ds_read_b128 v[56:59], v176 offset:34816
	ds_read_b128 v[64:67], v42 offset:64
	ds_read_b128 v[60:63], v176 offset:34880
	ds_read_b128 v[68:71], v177 offset:53248
	ds_read_b128 v[72:75], v177 offset:53312
	s_waitcnt lgkmcnt(1)
	v_mfma_f32_16x16x32_bf16 v[0:3], v[56:59], v[68:71], v[0:3]
	v_mul_f32_e64 v4, v4, v64
	v_mul_f32_e64 v5, v5, v65
	ds_read_b128 v[76:79], v176 offset:37120
	ds_read_b128 v[80:83], v42 offset:128
	v_pk_mul_f32 v[6:7], v[6:7], v[66:67]
	ds_read_b128 v[56:59], v176 offset:37184
	ds_read_b128 v[64:67], v42 offset:192
	s_waitcnt lgkmcnt(4)
	v_mfma_f32_16x16x32_bf16 v[0:3], v[60:63], v[72:75], v[0:3]
	ds_read_b128 v[60:63], v176 offset:39424
	s_waitcnt lgkmcnt(3)
	v_pk_mul_f32 v[8:9], v[8:9], v[80:81]
	v_pk_mul_f32 v[10:11], v[10:11], v[82:83]
	v_mfma_f32_16x16x32_bf16 v[4:7], v[76:79], v[68:71], v[4:7]
	ds_read_b128 v[76:79], v176 offset:39488
	s_waitcnt lgkmcnt(2)
	v_pk_mul_f32 v[16:17], v[16:17], v[64:65]
	v_pk_mul_f32 v[18:19], v[18:19], v[66:67]
	v_mfma_f32_16x16x32_bf16 v[4:7], v[56:59], v[72:75], v[4:7]
	ds_read_b128 v[56:59], v42 offset:256
	ds_read_b128 v[64:67], v176 offset:41728
	ds_read_b128 v[80:83], v176 offset:41792
	s_waitcnt lgkmcnt(2)
	v_pk_mul_f32 v[12:13], v[12:13], v[56:57]
	v_mfma_f32_16x16x32_bf16 v[8:11], v[60:63], v[68:71], v[8:11]
	ds_read_b128 v[60:63], v42 offset:320
	v_pk_mul_f32 v[14:15], v[14:15], v[58:59]
	s_waitcnt lgkmcnt(0)
	v_pk_mul_f32 v[24:25], v[24:25], v[60:61]
	v_mfma_f32_16x16x32_bf16 v[16:19], v[64:67], v[68:71], v[16:19]
	v_mul_f32_e64 v26, v26, v62
	v_mul_f32_e64 v27, v27, v63
	v_mfma_f32_16x16x32_bf16 v[8:11], v[76:79], v[72:75], v[8:11]
	ds_read_b128 v[56:59], v176 offset:44032
	ds_read_b128 v[76:79], v176 offset:44096
	ds_read_b128 v[60:63], v42 offset:384
	ds_read_b128 v[64:67], v176 offset:46336
	ds_read_b128 v[84:87], v176 offset:46400
	s_waitcnt lgkmcnt(2)
	v_pk_mul_f32 v[20:21], v[20:21], v[60:61]
	v_mfma_f32_16x16x32_bf16 v[16:19], v[80:83], v[72:75], v[16:19]
	ds_read_b128 v[80:83], v42 offset:448
	v_pk_mul_f32 v[22:23], v[22:23], v[62:63]
	s_waitcnt lgkmcnt(0)
	v_pk_mul_f32 v[28:29], v[28:29], v[80:81]
	v_mfma_f32_16x16x32_bf16 v[12:15], v[56:59], v[68:71], v[12:15]
	ds_read_b128 v[56:59], v176 offset:48640
	ds_read_b128 v[60:63], v176 offset:48704
	v_pk_mul_f32 v[30:31], v[30:31], v[82:83]
	v_mfma_f32_16x16x32_bf16 v[12:15], v[76:79], v[72:75], v[12:15]
	ds_read_b128 v[76:79], v176 offset:50944
	ds_read_b128 v[80:83], v176 offset:51008
	s_waitcnt lgkmcnt(0)
	s_barrier
; #define LAS __attribute__((address_space(3)))
; __device__ __forceinline__ unsigned pk2(float lo, float hi) { const f32x2 v = {lo, hi}; return __builtin_bit_cast(unsigned, __builtin_convertvector(v, bf16x2_t)); }
; __device__ __forceinline__ void hgrn_chain(LAS unsigned char* lds, int cid, bf16_t* P1, const float* hg_lb, bf16_t* Ob, int ldo, int ocbase, int ocdir) {
;     ...
;         for (int i = 0; i < 16; i += 2) *(LAS unsigned*)(VT + dcol * HLS + i0 + i) = (unsigned)rv[i] | ((unsigned)rv[i + 1] << 16);
;     ...
;         for (int nt = 0; nt < 8; ++nt) { u32x2 o; o.x = pk2(st[nt][0], st[nt][1]); o.y = pk2(st[nt][2], st[nt][3]); *(LAS u32x2*)(ST + (w * 16 + fr) * HLD + nt * 16 + fq * 4) = o; }
	v_mfma_f32_16x16x32_bf16 v[24:27], v[64:67], v[68:71], v[24:27]
	v_cvt_pk_bf16_f32 v64, v0, v1
	v_cvt_pk_bf16_f32 v65, v2, v3
	v_mfma_f32_16x16x32_bf16 v[20:23], v[56:59], v[68:71], v[20:23]
	v_cvt_pk_bf16_f32 v56, v8, v9
	v_cvt_pk_bf16_f32 v57, v10, v11
	v_cvt_pk_bf16_f32 v58, v16, v17
	v_mfma_f32_16x16x32_bf16 v[28:31], v[76:79], v[68:71], v[28:31]
	v_cvt_pk_bf16_f32 v59, v18, v19
	ds_write2_b64 v178, v[56:57], v[58:59] offset0:8 offset1:12
	v_cvt_pk_bf16_f32 v56, v12, v13
	v_mfma_f32_16x16x32_bf16 v[24:27], v[84:87], v[72:75], v[24:27]
	v_cvt_pk_bf16_f32 v57, v14, v15
	v_cvt_pk_bf16_f32 v66, v4, v5
	v_cvt_pk_bf16_f32 v67, v6, v7
	v_mfma_f32_16x16x32_bf16 v[20:23], v[60:63], v[72:75], v[20:23]
	ds_write2_b64 v178, v[64:65], v[66:67] offset1:4
	s_nop 2
	v_cvt_pk_bf16_f32 v58, v24, v25
	v_cvt_pk_bf16_f32 v59, v26, v27
	v_mfma_f32_16x16x32_bf16 v[28:31], v[80:83], v[72:75], v[28:31]
	ds_write2_b64 v178, v[56:57], v[58:59] offset0:16 offset1:20
	v_cvt_pk_bf16_f32 v56, v20, v21
	v_cvt_pk_bf16_f32 v57, v22, v23
	s_nop 4
	v_cvt_pk_bf16_f32 v58, v28, v29
	v_cvt_pk_bf16_f32 v59, v30, v31
	ds_write2_b64 v178, v[56:57], v[58:59] offset0:24 offset1:28
	s_cbranch_scc0 .LBB0_1711
	s_waitcnt vmcnt(6)
	v_lshl_or_b32 v32, v236, 16, v235
	v_lshl_or_b32 v33, v238, 16, v237
	v_lshl_or_b32 v34, v240, 16, v239
	v_lshl_or_b32 v35, v242, 16, v241
	v_lshl_or_b32 v36, v244, 16, v243
	v_lshl_or_b32 v39, v246, 16, v245
	v_lshl_or_b32 v37, v248, 16, v247
	v_lshl_or_b32 v38, v250, 16, v249

; __device__ __forceinline__ unsigned xb_add(unsigned* p, unsigned v) { return __hip_atomic_fetch_add(p, v, __ATOMIC_RELAXED, __HIP_MEMORY_SCOPE_AGENT); }
; #define INP(k) (*(const float* const volatile __attribute__((address_space(4)))*)(ka + 8 * (k)))
; #define PHASE(k) for (int rep_ = 0; rep_ < (IN(k) ? REPS(k) : 0); ++rep_, ((REPS(k) > 1) ? (grid.sync(), 0) : 0))
; #define SEAM(k) do { if (IN(k) && IN((k) + 1)) xcd_barrier(xbar); } while (0)
; __device__ __forceinline__ void xcd_barrier(const XcdBarrier& b) {
;     asm volatile("s_waitcnt vmcnt(0)" ::: "memory");
;     __syncthreads();
;     if (threadIdx.x == 0) {
;         unsigned* bar = b.bar;
;         __builtin_amdgcn_s_waitcnt(0);
;         unsigned nloc = b.st[0], nx = b.st[1];
;         if (nloc == 0u) { xcd_barrier_complete(bar, b.x, nloc, nx); b.st[0] = nloc; b.st[1] = nx; }
;         const unsigned old = xb_add(&bar[XB_XSUB(b.x)], 1u);
;         const unsigned gen = old / nloc;
; __global__ void __launch_bounds__(512, 2) mk_fwd(Args args) {
;     ...
;     PHASE(11) { for (int cid = bx; cid < 256; cid += G) hgrn_chain(lds, cid, P, INP(25), P, HGP, 1024, 1024); }
;     SEAM(11);
.LBB0_1720:
	s_setprio 0
	v_readlane_b32 s0, v253, 23
	s_cmp_gt_i32 s0, 12
	s_cselect_b64 s[0:1], -1, 0
	s_and_b64 s[2:3], s[28:29], s[0:1]
	s_and_b64 vcc, exec, s[2:3]
	s_cbranch_vccz .LBB0_1774
	s_waitcnt vmcnt(0)
	s_waitcnt vmcnt(0) lgkmcnt(0)
	s_barrier
	s_mov_b64 s[2:3], exec
	v_readlane_b32 s4, v253, 6
	v_readlane_b32 s5, v253, 7
	s_and_b64 s[4:5], s[2:3], s[4:5]
	s_mov_b64 exec, s[4:5]
	s_cbranch_execz .LBB0_1773
	s_add_i32 s4, 0, 0x27ff0
	v_mov_b32_e32 v0, s4
	s_waitcnt vmcnt(0) expcnt(0) lgkmcnt(0)
	ds_read_b32 v2, v0
	s_add_i32 s4, 0, 0x27ff4
	v_mov_b32_e32 v0, s4
	ds_read_b32 v0, v0
	s_waitcnt lgkmcnt(1)
	v_cmp_ne_u32_e32 vcc, 0, v2
	s_cbranch_vccnz .LBB0_1737
	v_readlane_b32 s4, v253, 2
	v_readlane_b32 s10, v253, 0
	s_mul_i32 s18, s4, s96
	v_readlane_b32 s11, v253, 1
	s_add_u32 s4, s10, 0x1000
	s_addc_u32 s5, s11, 0
	s_add_u32 s6, s10, 0x1100
	s_addc_u32 s7, s11, 0
	s_add_u32 s8, s10, 0x1200
	s_addc_u32 s9, s11, 0
	s_add_u32 s10, s10, 0x1300
	s_mul_i32 s18, s18, s97
	s_addc_u32 s11, s11, 0
	s_mov_b32 s19, 1
	v_mov_b32_e32 v16, 0
	s_branch .LBB0_1725
